# NSA compression MLP K-loop: weight fragments fetched as even/odd k-step pairs back to back (full cache lines in adjacent loads) with two pairs of lookahead
# baseline (speedup 1.0000x reference)
; #define MFMA16(a, b, c) __builtin_amdgcn_mfma_f32_16x16x32_bf16((a), (b), (c), 0, 0, 0)
; __device__ __forceinline__ void item_cmpk(const bf16_t* qkv, const bf16_t* Wb, const float* hb, bf16_t* KC, int it, int wsub) {
;     int tid_ = threadIdx.x; asm volatile("" : "+v"(tid_));
;     const int lane = tid_ & 63, wid = wsub, c = lane & 15, g = lane >> 4;
;     const int ty = it & 1, gk = (it >> 1) & 1, b = it >> 2;
;     const int n = 16 * wid + c, nn = n < 127 ? n : 126;
;     const bf16_t* src = qkv + ((size_t)b * SEQ + 16 * nn) * QP + (ty ? C_BVC : C_BKC) + gk * 64 + g * 8;
;     const bf16_t* w1t = Wb + W_1 + (size_t)ty * 128 * 2048 + (size_t)c * 2048 + g * 8;
;     f32x4 hT[8];
; #pragma unroll
;     for (int ht = 0; ht < 8; ++ht) hT[ht] = (f32x4){0.f, 0.f, 0.f, 0.f};
; #pragma unroll 2
;     for (int ks = 0; ks < 64; ++ks) {
;         const bf16x8 bfrag = *(const bf16x8*)(src + (size_t)(ks >> 1) * QP + (ks & 1) * 32);
; #pragma unroll
;         for (int ht = 0; ht < 8; ++ht) { const bf16x8 afrag = *(const bf16x8*)(w1t + (size_t)ht * 16 * 2048 + ks * 32); hT[ht] = MFMA16(afrag, bfrag, hT[ht]); }
;     }
.LBB0_348:
	s_andn2_b64 vcc, exec, s[0:1]
	s_cbranch_vccnz .LBB0_247
	v_mov_b32_e32 v2, v214
	s_lshl_b32 s0, s26, 4
	s_ashr_i32 s8, s26, 3
	s_ashr_i32 s4, s26, 5
	v_and_b32_e32 v45, 15, v2
	s_and_b32 s0, s0, 0x70
	s_and_b32 s6, s8, 1
	s_lshr_b32 s7, s8, 1
	v_or_b32_e32 v1, s0, v45
	s_ashr_i32 s5, s4, 31
	s_movk_i32 s0, 0x7f
	v_cmp_ne_u32_e32 vcc, s0, v1
	s_cmp_eq_u32 s6, 0
	s_movk_i32 s0, 0xa00
	v_readlane_b32 s16, v252, 4
	s_cselect_b32 s9, s0, 0xb00
	s_lshl_b32 s0, s6, 19
	v_readlane_b32 s20, v252, 8
	v_readlane_b32 s21, v252, 9
	s_add_u32 s0, s20, s0
	s_addc_u32 s1, s21, 0
	s_lshl_b32 s8, s8, 6
	s_and_b32 s8, s8, 0x80
	s_add_u32 s9, s20, s9
	v_lshlrev_b32_e32 v3, 4, v1
	v_mov_b32_e32 v8, 0x7e0
	s_addc_u32 s10, s21, 0
	v_cndmask_b32_e32 v10, v8, v3, vcc
	v_lshlrev_b32_e32 v8, 12, v45
	v_mov_b32_e32 v9, v0
	s_add_u32 s8, s9, s8
	s_mul_i32 s0, s4, 0xe18000
	s_addc_u32 s9, s10, 0
	s_mul_hi_i32 s1, s4, 0xe18000
	s_add_u32 s0, s8, s0
	s_addc_u32 s1, s9, s1
	s_add_u32 s72, s0, 0x0c000000
	s_addc_u32 s73, s1, 0
	v_mul_lo_u32 v55, v10, s85
	v_mov_b32_e32 v8, 0
	v_lshrrev_b32_e32 v44, 4, v2
	v_and_b32_e32 v2, 48, v2
	v_mov_b32_e32 v3, v0
	s_mov_b32 s8, 64
	v_mov_b32_e32 v9, v8
	v_mov_b32_e32 v10, v8
	v_mov_b32_e32 v11, v8
	v_mov_b32_e32 v36, v8
	v_mov_b32_e32 v37, v8
	v_mov_b32_e32 v38, v8
	v_mov_b32_e32 v39, v8
	v_mov_b32_e32 v32, v8
	v_mov_b32_e32 v33, v8
	v_mov_b32_e32 v34, v8
	v_mov_b32_e32 v35, v8
	v_mov_b32_e32 v28, v8
	v_mov_b32_e32 v29, v8
	v_mov_b32_e32 v30, v8
	v_mov_b32_e32 v31, v8
	v_mov_b32_e32 v24, v8
	v_mov_b32_e32 v25, v8
	v_mov_b32_e32 v26, v8
	v_mov_b32_e32 v27, v8
	v_mov_b32_e32 v20, v8
	v_mov_b32_e32 v21, v8
	v_mov_b32_e32 v22, v8
	v_mov_b32_e32 v23, v8
	v_mov_b32_e32 v16, v8
	v_mov_b32_e32 v17, v8
	v_mov_b32_e32 v18, v8
	v_mov_b32_e32 v19, v8
	v_mov_b32_e32 v12, v8
	v_mov_b32_e32 v13, v8
	v_mov_b32_e32 v14, v8
	v_mov_b32_e32 v15, v8
	s_brev_b32 s9, 48
	v_readlane_b32 s17, v252, 5
	v_readlane_b32 s18, v252, 6
	v_readlane_b32 s19, v252, 7
	v_readlane_b32 s22, v252, 10
	v_readlane_b32 s23, v252, 11
	v_add_u32_e32 v55, v55, v2
	v_lshl_or_b32 v54, v45, 12, v2
	s_lshl_b32 s74, s6, 19
	s_add_u32 s74, s74, 0x3d80000
	s_add_u32 s56, s20, s74
	s_addc_u32 s57, s21, 0
	s_add_u32 s58, s56, 0x10000
	s_addc_u32 s59, s57, 0
	s_add_u32 s60, s58, 0x10000
	s_addc_u32 s61, s59, 0
	s_add_u32 s62, s60, 0x10000
	s_addc_u32 s63, s61, 0
	s_add_u32 s64, s62, 0x10000
	s_addc_u32 s65, s63, 0
	s_add_u32 s66, s64, 0x10000
	s_addc_u32 s67, s65, 0
	s_add_u32 s68, s66, 0x10000
	s_addc_u32 s69, s67, 0
	s_add_u32 s70, s68, 0x10000
	s_addc_u32 s71, s69, 0
	global_load_dwordx4 v[46:49], v55, s[72:73]
	global_load_dwordx4 v[190:193], v55, s[72:73] offset:64
	global_load_dwordx4 v[62:65], v54, s[56:57]
	global_load_dwordx4 v[66:69], v54, s[56:57] offset:64
	global_load_dwordx4 v[70:73], v54, s[58:59]
	global_load_dwordx4 v[74:77], v54, s[58:59] offset:64
	global_load_dwordx4 v[78:81], v54, s[60:61]
	global_load_dwordx4 v[82:85], v54, s[60:61] offset:64
	global_load_dwordx4 v[86:89], v54, s[62:63]
	global_load_dwordx4 v[90:93], v54, s[62:63] offset:64
	global_load_dwordx4 v[94:97], v54, s[64:65]
	global_load_dwordx4 v[98:101], v54, s[64:65] offset:64
	global_load_dwordx4 v[102:105], v54, s[66:67]
	global_load_dwordx4 v[106:109], v54, s[66:67] offset:64
	global_load_dwordx4 v[110:113], v54, s[68:69]
	global_load_dwordx4 v[114:117], v54, s[68:69] offset:64
	global_load_dwordx4 v[118:121], v54, s[70:71]
	global_load_dwordx4 v[122:125], v54, s[70:71] offset:64
	v_add_u32_e32 v55, 0x1c30, v55
	global_load_dwordx4 v[50:53], v55, s[72:73]
	global_load_dwordx4 v[194:197], v55, s[72:73] offset:64
	global_load_dwordx4 v[126:129], v54, s[56:57] offset:128
	global_load_dwordx4 v[130:133], v54, s[56:57] offset:192
	global_load_dwordx4 v[134:137], v54, s[58:59] offset:128
	global_load_dwordx4 v[138:141], v54, s[58:59] offset:192
	global_load_dwordx4 v[142:145], v54, s[60:61] offset:128
	global_load_dwordx4 v[146:149], v54, s[60:61] offset:192
	global_load_dwordx4 v[150:153], v54, s[62:63] offset:128
	global_load_dwordx4 v[154:157], v54, s[62:63] offset:192
	global_load_dwordx4 v[158:161], v54, s[64:65] offset:128
	global_load_dwordx4 v[162:165], v54, s[64:65] offset:192
	global_load_dwordx4 v[166:169], v54, s[66:67] offset:128
	global_load_dwordx4 v[170:173], v54, s[66:67] offset:192
	global_load_dwordx4 v[174:177], v54, s[68:69] offset:128
	global_load_dwordx4 v[178:181], v54, s[68:69] offset:192
	global_load_dwordx4 v[182:185], v54, s[70:71] offset:128
	global_load_dwordx4 v[186:189], v54, s[70:71] offset:192
	v_add_u32_e32 v55, 0x1c30, v55
	v_add_u32_e32 v54, 0x100, v54
	s_movk_i32 s8, 7
; #define MFMA16(a, b, c) __builtin_amdgcn_mfma_f32_16x16x32_bf16((a), (b), (c), 0, 0, 0)
; __device__ __forceinline__ void item_cmpk(const bf16_t* qkv, const bf16_t* Wb, const float* hb, bf16_t* KC, int it, int wsub) {
;     ...
; #pragma unroll 2
;     for (int ks = 0; ks < 64; ++ks) {
;         const bf16x8 bfrag = *(const bf16x8*)(src + (size_t)(ks >> 1) * QP + (ks & 1) * 32);
; #pragma unroll
;         for (int ht = 0; ht < 8; ++ht) { const bf16x8 afrag = *(const bf16x8*)(w1t + (size_t)ht * 16 * 2048 + ks * 32); hT[ht] = MFMA16(afrag, bfrag, hT[ht]); }
;     }
.Lcmpk2_loop:
	s_waitcnt vmcnt(33)
	v_mfma_f32_16x16x32_bf16 v[36:39], v[62:65], v[46:49], v[36:39]
	s_waitcnt vmcnt(31)
	v_mfma_f32_16x16x32_bf16 v[32:35], v[70:73], v[46:49], v[32:35]
	s_waitcnt vmcnt(29)
	v_mfma_f32_16x16x32_bf16 v[28:31], v[78:81], v[46:49], v[28:31]
	s_waitcnt vmcnt(27)
	v_mfma_f32_16x16x32_bf16 v[24:27], v[86:89], v[46:49], v[24:27]
	s_waitcnt vmcnt(25)
	v_mfma_f32_16x16x32_bf16 v[20:23], v[94:97], v[46:49], v[20:23]
	s_waitcnt vmcnt(23)
	v_mfma_f32_16x16x32_bf16 v[16:19], v[102:105], v[46:49], v[16:19]
	s_waitcnt vmcnt(21)
	v_mfma_f32_16x16x32_bf16 v[12:15], v[110:113], v[46:49], v[12:15]
	s_waitcnt vmcnt(19)
	v_mfma_f32_16x16x32_bf16 v[8:11], v[118:121], v[46:49], v[8:11]
	global_load_dwordx4 v[198:201], v55, s[72:73]
	global_load_dwordx4 v[202:205], v55, s[72:73] offset:64
	s_waitcnt vmcnt(34)
	v_mfma_f32_16x16x32_bf16 v[36:39], v[66:69], v[190:193], v[36:39]
	global_load_dwordx4 v[62:65], v54, s[56:57]
	global_load_dwordx4 v[66:69], v54, s[56:57] offset:64
	s_waitcnt vmcnt(34)
	v_mfma_f32_16x16x32_bf16 v[32:35], v[74:77], v[190:193], v[32:35]
	global_load_dwordx4 v[70:73], v54, s[58:59]
	global_load_dwordx4 v[74:77], v54, s[58:59] offset:64
	s_waitcnt vmcnt(34)
	v_mfma_f32_16x16x32_bf16 v[28:31], v[82:85], v[190:193], v[28:31]
	global_load_dwordx4 v[78:81], v54, s[60:61]
	global_load_dwordx4 v[82:85], v54, s[60:61] offset:64
	s_waitcnt vmcnt(34)
	v_mfma_f32_16x16x32_bf16 v[24:27], v[90:93], v[190:193], v[24:27]
	global_load_dwordx4 v[86:89], v54, s[62:63]
	global_load_dwordx4 v[90:93], v54, s[62:63] offset:64
	s_waitcnt vmcnt(34)
	v_mfma_f32_16x16x32_bf16 v[20:23], v[98:101], v[190:193], v[20:23]
	global_load_dwordx4 v[94:97], v54, s[64:65]
	global_load_dwordx4 v[98:101], v54, s[64:65] offset:64
	s_waitcnt vmcnt(34)
	v_mfma_f32_16x16x32_bf16 v[16:19], v[106:109], v[190:193], v[16:19]
	global_load_dwordx4 v[102:105], v54, s[66:67]
	global_load_dwordx4 v[106:109], v54, s[66:67] offset:64
	s_waitcnt vmcnt(34)
	v_mfma_f32_16x16x32_bf16 v[12:15], v[114:117], v[190:193], v[12:15]
	global_load_dwordx4 v[110:113], v54, s[68:69]
	global_load_dwordx4 v[114:117], v54, s[68:69] offset:64
	s_waitcnt vmcnt(34)
	v_mfma_f32_16x16x32_bf16 v[8:11], v[122:125], v[190:193], v[8:11]
	global_load_dwordx4 v[118:121], v54, s[70:71]
	global_load_dwordx4 v[122:125], v54, s[70:71] offset:64
	v_add_u32_e32 v55, 0x1c30, v55
	s_waitcnt vmcnt(33)
	v_mfma_f32_16x16x32_bf16 v[36:39], v[126:129], v[50:53], v[36:39]
	s_waitcnt vmcnt(31)
	v_mfma_f32_16x16x32_bf16 v[32:35], v[134:137], v[50:53], v[32:35]
	s_waitcnt vmcnt(29)
	v_mfma_f32_16x16x32_bf16 v[28:31], v[142:145], v[50:53], v[28:31]
	s_waitcnt vmcnt(27)
	v_mfma_f32_16x16x32_bf16 v[24:27], v[150:153], v[50:53], v[24:27]
	s_waitcnt vmcnt(25)
	v_mfma_f32_16x16x32_bf16 v[20:23], v[158:161], v[50:53], v[20:23]
	s_waitcnt vmcnt(23)
	v_mfma_f32_16x16x32_bf16 v[16:19], v[166:169], v[50:53], v[16:19]
	s_waitcnt vmcnt(21)
	v_mfma_f32_16x16x32_bf16 v[12:15], v[174:177], v[50:53], v[12:15]
	s_waitcnt vmcnt(19)
	v_mfma_f32_16x16x32_bf16 v[8:11], v[182:185], v[50:53], v[8:11]
	global_load_dwordx4 v[206:209], v55, s[72:73]
	global_load_dwordx4 v[210:213], v55, s[72:73] offset:64
	s_waitcnt vmcnt(34)
	v_mfma_f32_16x16x32_bf16 v[36:39], v[130:133], v[194:197], v[36:39]
	global_load_dwordx4 v[126:129], v54, s[56:57] offset:128
	global_load_dwordx4 v[130:133], v54, s[56:57] offset:192
	s_waitcnt vmcnt(34)
	v_mfma_f32_16x16x32_bf16 v[32:35], v[138:141], v[194:197], v[32:35]
	global_load_dwordx4 v[134:137], v54, s[58:59] offset:128
	global_load_dwordx4 v[138:141], v54, s[58:59] offset:192
	s_waitcnt vmcnt(34)
	v_mfma_f32_16x16x32_bf16 v[28:31], v[146:149], v[194:197], v[28:31]
	global_load_dwordx4 v[142:145], v54, s[60:61] offset:128
	global_load_dwordx4 v[146:149], v54, s[60:61] offset:192
	s_waitcnt vmcnt(34)
	v_mfma_f32_16x16x32_bf16 v[24:27], v[154:157], v[194:197], v[24:27]
	global_load_dwordx4 v[150:153], v54, s[62:63] offset:128
	global_load_dwordx4 v[154:157], v54, s[62:63] offset:192
	s_waitcnt vmcnt(34)
	v_mfma_f32_16x16x32_bf16 v[20:23], v[162:165], v[194:197], v[20:23]
	global_load_dwordx4 v[158:161], v54, s[64:65] offset:128
	global_load_dwordx4 v[162:165], v54, s[64:65] offset:192
	s_waitcnt vmcnt(34)
	v_mfma_f32_16x16x32_bf16 v[16:19], v[170:173], v[194:197], v[16:19]
	global_load_dwordx4 v[166:169], v54, s[66:67] offset:128
	global_load_dwordx4 v[170:173], v54, s[66:67] offset:192
	s_waitcnt vmcnt(34)
	v_mfma_f32_16x16x32_bf16 v[12:15], v[178:181], v[194:197], v[12:15]
	global_load_dwordx4 v[174:177], v54, s[68:69] offset:128
	global_load_dwordx4 v[178:181], v54, s[68:69] offset:192
	s_waitcnt vmcnt(34)
	v_mfma_f32_16x16x32_bf16 v[8:11], v[186:189], v[194:197], v[8:11]
	global_load_dwordx4 v[182:185], v54, s[70:71] offset:128
	global_load_dwordx4 v[186:189], v54, s[70:71] offset:192
	v_add_u32_e32 v55, 0x1c30, v55
	s_waitcnt vmcnt(33)
	v_mfma_f32_16x16x32_bf16 v[36:39], v[62:65], v[198:201], v[36:39]
	s_waitcnt vmcnt(31)
	v_mfma_f32_16x16x32_bf16 v[32:35], v[70:73], v[198:201], v[32:35]
	s_waitcnt vmcnt(29)
	v_mfma_f32_16x16x32_bf16 v[28:31], v[78:81], v[198:201], v[28:31]
	s_waitcnt vmcnt(27)
	v_mfma_f32_16x16x32_bf16 v[24:27], v[86:89], v[198:201], v[24:27]
	s_waitcnt vmcnt(25)
	v_mfma_f32_16x16x32_bf16 v[20:23], v[94:97], v[198:201], v[20:23]
	s_waitcnt vmcnt(23)
	v_mfma_f32_16x16x32_bf16 v[16:19], v[102:105], v[198:201], v[16:19]
	s_waitcnt vmcnt(21)
	v_mfma_f32_16x16x32_bf16 v[12:15], v[110:113], v[198:201], v[12:15]
	s_waitcnt vmcnt(19)
	v_mfma_f32_16x16x32_bf16 v[8:11], v[118:121], v[198:201], v[8:11]
	global_load_dwordx4 v[46:49], v55, s[72:73]
	global_load_dwordx4 v[190:193], v55, s[72:73] offset:64
	s_waitcnt vmcnt(34)
; #define MFMA16(a, b, c) __builtin_amdgcn_mfma_f32_16x16x32_bf16((a), (b), (c), 0, 0, 0)
; __device__ __forceinline__ void item_cmpk(const bf16_t* qkv, const bf16_t* Wb, const float* hb, bf16_t* KC, int it, int wsub) {
;     ...
; #pragma unroll 2
;     for (int ks = 0; ks < 64; ++ks) {
;         const bf16x8 bfrag = *(const bf16x8*)(src + (size_t)(ks >> 1) * QP + (ks & 1) * 32);
; #pragma unroll
;         for (int ht = 0; ht < 8; ++ht) { const bf16x8 afrag = *(const bf16x8*)(w1t + (size_t)ht * 16 * 2048 + ks * 32); hT[ht] = MFMA16(afrag, bfrag, hT[ht]); }
;     }
	v_mfma_f32_16x16x32_bf16 v[36:39], v[66:69], v[202:205], v[36:39]
	global_load_dwordx4 v[62:65], v54, s[56:57] offset:256
	global_load_dwordx4 v[66:69], v54, s[56:57] offset:320
	s_waitcnt vmcnt(34)
	v_mfma_f32_16x16x32_bf16 v[32:35], v[74:77], v[202:205], v[32:35]
	global_load_dwordx4 v[70:73], v54, s[58:59] offset:256
	global_load_dwordx4 v[74:77], v54, s[58:59] offset:320
	s_waitcnt vmcnt(34)
	v_mfma_f32_16x16x32_bf16 v[28:31], v[82:85], v[202:205], v[28:31]
	global_load_dwordx4 v[78:81], v54, s[60:61] offset:256
	global_load_dwordx4 v[82:85], v54, s[60:61] offset:320
	s_waitcnt vmcnt(34)
	v_mfma_f32_16x16x32_bf16 v[24:27], v[90:93], v[202:205], v[24:27]
	global_load_dwordx4 v[86:89], v54, s[62:63] offset:256
	global_load_dwordx4 v[90:93], v54, s[62:63] offset:320
	s_waitcnt vmcnt(34)
	v_mfma_f32_16x16x32_bf16 v[20:23], v[98:101], v[202:205], v[20:23]
	global_load_dwordx4 v[94:97], v54, s[64:65] offset:256
	global_load_dwordx4 v[98:101], v54, s[64:65] offset:320
	s_waitcnt vmcnt(34)
	v_mfma_f32_16x16x32_bf16 v[16:19], v[106:109], v[202:205], v[16:19]
	global_load_dwordx4 v[102:105], v54, s[66:67] offset:256
	global_load_dwordx4 v[106:109], v54, s[66:67] offset:320
	s_waitcnt vmcnt(34)
	v_mfma_f32_16x16x32_bf16 v[12:15], v[114:117], v[202:205], v[12:15]
	global_load_dwordx4 v[110:113], v54, s[68:69] offset:256
	global_load_dwordx4 v[114:117], v54, s[68:69] offset:320
	s_waitcnt vmcnt(34)
	v_mfma_f32_16x16x32_bf16 v[8:11], v[122:125], v[202:205], v[8:11]
	global_load_dwordx4 v[118:121], v54, s[70:71] offset:256
	global_load_dwordx4 v[122:125], v54, s[70:71] offset:320
	v_add_u32_e32 v55, 0x1c30, v55
	s_waitcnt vmcnt(33)
	v_mfma_f32_16x16x32_bf16 v[36:39], v[126:129], v[206:209], v[36:39]
	s_waitcnt vmcnt(31)
	v_mfma_f32_16x16x32_bf16 v[32:35], v[134:137], v[206:209], v[32:35]
	s_waitcnt vmcnt(29)
	v_mfma_f32_16x16x32_bf16 v[28:31], v[142:145], v[206:209], v[28:31]
	s_waitcnt vmcnt(27)
	v_mfma_f32_16x16x32_bf16 v[24:27], v[150:153], v[206:209], v[24:27]
	s_waitcnt vmcnt(25)
	v_mfma_f32_16x16x32_bf16 v[20:23], v[158:161], v[206:209], v[20:23]
	s_waitcnt vmcnt(23)
	v_mfma_f32_16x16x32_bf16 v[16:19], v[166:169], v[206:209], v[16:19]
	s_waitcnt vmcnt(21)
	v_mfma_f32_16x16x32_bf16 v[12:15], v[174:177], v[206:209], v[12:15]
	s_waitcnt vmcnt(19)
	v_mfma_f32_16x16x32_bf16 v[8:11], v[182:185], v[206:209], v[8:11]
	global_load_dwordx4 v[50:53], v55, s[72:73]
	global_load_dwordx4 v[194:197], v55, s[72:73] offset:64
	s_waitcnt vmcnt(34)
	v_mfma_f32_16x16x32_bf16 v[36:39], v[130:133], v[210:213], v[36:39]
	global_load_dwordx4 v[126:129], v54, s[56:57] offset:384
	global_load_dwordx4 v[130:133], v54, s[56:57] offset:448
	s_waitcnt vmcnt(34)
	v_mfma_f32_16x16x32_bf16 v[32:35], v[138:141], v[210:213], v[32:35]
	global_load_dwordx4 v[134:137], v54, s[58:59] offset:384
	global_load_dwordx4 v[138:141], v54, s[58:59] offset:448
	s_waitcnt vmcnt(34)
	v_mfma_f32_16x16x32_bf16 v[28:31], v[146:149], v[210:213], v[28:31]
	global_load_dwordx4 v[142:145], v54, s[60:61] offset:384
	global_load_dwordx4 v[146:149], v54, s[60:61] offset:448
	s_waitcnt vmcnt(34)
	v_mfma_f32_16x16x32_bf16 v[24:27], v[154:157], v[210:213], v[24:27]
	global_load_dwordx4 v[150:153], v54, s[62:63] offset:384
	global_load_dwordx4 v[154:157], v54, s[62:63] offset:448
	s_waitcnt vmcnt(34)
	v_mfma_f32_16x16x32_bf16 v[20:23], v[162:165], v[210:213], v[20:23]
	global_load_dwordx4 v[158:161], v54, s[64:65] offset:384
	global_load_dwordx4 v[162:165], v54, s[64:65] offset:448
	s_waitcnt vmcnt(34)
	v_mfma_f32_16x16x32_bf16 v[16:19], v[170:173], v[210:213], v[16:19]
	global_load_dwordx4 v[166:169], v54, s[66:67] offset:384
	global_load_dwordx4 v[170:173], v54, s[66:67] offset:448
	s_waitcnt vmcnt(34)
	v_mfma_f32_16x16x32_bf16 v[12:15], v[178:181], v[210:213], v[12:15]
	global_load_dwordx4 v[174:177], v54, s[68:69] offset:384
	global_load_dwordx4 v[178:181], v54, s[68:69] offset:448
	s_waitcnt vmcnt(34)
	v_mfma_f32_16x16x32_bf16 v[8:11], v[186:189], v[210:213], v[8:11]
	global_load_dwordx4 v[182:185], v54, s[70:71] offset:384
	global_load_dwordx4 v[186:189], v54, s[70:71] offset:448
	v_add_u32_e32 v55, 0x1c30, v55
	v_add_u32_e32 v54, 0x200, v54
	s_add_i32 s8, s8, -1
	s_cmp_lg_u32 s8, 0
	s_cbranch_scc1 .Lcmpk2_loop
	s_waitcnt vmcnt(33)
	v_mfma_f32_16x16x32_bf16 v[36:39], v[62:65], v[46:49], v[36:39]
	s_waitcnt vmcnt(31)
	v_mfma_f32_16x16x32_bf16 v[32:35], v[70:73], v[46:49], v[32:35]
	s_waitcnt vmcnt(29)
	v_mfma_f32_16x16x32_bf16 v[28:31], v[78:81], v[46:49], v[28:31]
	s_waitcnt vmcnt(27)
	v_mfma_f32_16x16x32_bf16 v[24:27], v[86:89], v[46:49], v[24:27]
	s_waitcnt vmcnt(25)
	v_mfma_f32_16x16x32_bf16 v[20:23], v[94:97], v[46:49], v[20:23]
	s_waitcnt vmcnt(23)
	v_mfma_f32_16x16x32_bf16 v[16:19], v[102:105], v[46:49], v[16:19]
	s_waitcnt vmcnt(21)
	v_mfma_f32_16x16x32_bf16 v[12:15], v[110:113], v[46:49], v[12:15]
	s_waitcnt vmcnt(19)
	v_mfma_f32_16x16x32_bf16 v[8:11], v[118:121], v[46:49], v[8:11]
	global_load_dwordx4 v[198:201], v55, s[72:73]
	global_load_dwordx4 v[202:205], v55, s[72:73] offset:64
	s_waitcnt vmcnt(34)
	v_mfma_f32_16x16x32_bf16 v[36:39], v[66:69], v[190:193], v[36:39]
	global_load_dwordx4 v[62:65], v54, s[56:57]
	global_load_dwordx4 v[66:69], v54, s[56:57] offset:64
	s_waitcnt vmcnt(34)
	v_mfma_f32_16x16x32_bf16 v[32:35], v[74:77], v[190:193], v[32:35]
	global_load_dwordx4 v[70:73], v54, s[58:59]
	global_load_dwordx4 v[74:77], v54, s[58:59] offset:64
	s_waitcnt vmcnt(34)
	v_mfma_f32_16x16x32_bf16 v[28:31], v[82:85], v[190:193], v[28:31]
	global_load_dwordx4 v[78:81], v54, s[60:61]
	global_load_dwordx4 v[82:85], v54, s[60:61] offset:64
	s_waitcnt vmcnt(34)
; #define MFMA16(a, b, c) __builtin_amdgcn_mfma_f32_16x16x32_bf16((a), (b), (c), 0, 0, 0)
; __device__ __forceinline__ void item_cmpk(const bf16_t* qkv, const bf16_t* Wb, const float* hb, bf16_t* KC, int it, int wsub) {
;     ...
; #pragma unroll 2
;     for (int ks = 0; ks < 64; ++ks) {
;         const bf16x8 bfrag = *(const bf16x8*)(src + (size_t)(ks >> 1) * QP + (ks & 1) * 32);
; #pragma unroll
;         for (int ht = 0; ht < 8; ++ht) { const bf16x8 afrag = *(const bf16x8*)(w1t + (size_t)ht * 16 * 2048 + ks * 32); hT[ht] = MFMA16(afrag, bfrag, hT[ht]); }
;     }
	v_mfma_f32_16x16x32_bf16 v[24:27], v[90:93], v[190:193], v[24:27]
	global_load_dwordx4 v[86:89], v54, s[62:63]
	global_load_dwordx4 v[90:93], v54, s[62:63] offset:64
	s_waitcnt vmcnt(34)
	v_mfma_f32_16x16x32_bf16 v[20:23], v[98:101], v[190:193], v[20:23]
	global_load_dwordx4 v[94:97], v54, s[64:65]
	global_load_dwordx4 v[98:101], v54, s[64:65] offset:64
	s_waitcnt vmcnt(34)
	v_mfma_f32_16x16x32_bf16 v[16:19], v[106:109], v[190:193], v[16:19]
	global_load_dwordx4 v[102:105], v54, s[66:67]
	global_load_dwordx4 v[106:109], v54, s[66:67] offset:64
	s_waitcnt vmcnt(34)
	v_mfma_f32_16x16x32_bf16 v[12:15], v[114:117], v[190:193], v[12:15]
	global_load_dwordx4 v[110:113], v54, s[68:69]
	global_load_dwordx4 v[114:117], v54, s[68:69] offset:64
	s_waitcnt vmcnt(34)
	v_mfma_f32_16x16x32_bf16 v[8:11], v[122:125], v[190:193], v[8:11]
	global_load_dwordx4 v[118:121], v54, s[70:71]
	global_load_dwordx4 v[122:125], v54, s[70:71] offset:64
	v_add_u32_e32 v55, 0x1c30, v55
	s_waitcnt vmcnt(33)
	v_mfma_f32_16x16x32_bf16 v[36:39], v[126:129], v[50:53], v[36:39]
	s_waitcnt vmcnt(31)
	v_mfma_f32_16x16x32_bf16 v[32:35], v[134:137], v[50:53], v[32:35]
	s_waitcnt vmcnt(29)
	v_mfma_f32_16x16x32_bf16 v[28:31], v[142:145], v[50:53], v[28:31]
	s_waitcnt vmcnt(27)
	v_mfma_f32_16x16x32_bf16 v[24:27], v[150:153], v[50:53], v[24:27]
	s_waitcnt vmcnt(25)
	v_mfma_f32_16x16x32_bf16 v[20:23], v[158:161], v[50:53], v[20:23]
	s_waitcnt vmcnt(23)
	v_mfma_f32_16x16x32_bf16 v[16:19], v[166:169], v[50:53], v[16:19]
	s_waitcnt vmcnt(21)
	v_mfma_f32_16x16x32_bf16 v[12:15], v[174:177], v[50:53], v[12:15]
	s_waitcnt vmcnt(19)
	v_mfma_f32_16x16x32_bf16 v[8:11], v[182:185], v[50:53], v[8:11]
	global_load_dwordx4 v[206:209], v55, s[72:73]
	global_load_dwordx4 v[210:213], v55, s[72:73] offset:64
	s_waitcnt vmcnt(34)
	v_mfma_f32_16x16x32_bf16 v[36:39], v[130:133], v[194:197], v[36:39]
	global_load_dwordx4 v[126:129], v54, s[56:57] offset:128
	global_load_dwordx4 v[130:133], v54, s[56:57] offset:192
	s_waitcnt vmcnt(34)
	v_mfma_f32_16x16x32_bf16 v[32:35], v[138:141], v[194:197], v[32:35]
	global_load_dwordx4 v[134:137], v54, s[58:59] offset:128
	global_load_dwordx4 v[138:141], v54, s[58:59] offset:192
	s_waitcnt vmcnt(34)
	v_mfma_f32_16x16x32_bf16 v[28:31], v[146:149], v[194:197], v[28:31]
	global_load_dwordx4 v[142:145], v54, s[60:61] offset:128
	global_load_dwordx4 v[146:149], v54, s[60:61] offset:192
	s_waitcnt vmcnt(34)
	v_mfma_f32_16x16x32_bf16 v[24:27], v[154:157], v[194:197], v[24:27]
	global_load_dwordx4 v[150:153], v54, s[62:63] offset:128
	global_load_dwordx4 v[154:157], v54, s[62:63] offset:192
	s_waitcnt vmcnt(34)
	v_mfma_f32_16x16x32_bf16 v[20:23], v[162:165], v[194:197], v[20:23]
	global_load_dwordx4 v[158:161], v54, s[64:65] offset:128
	global_load_dwordx4 v[162:165], v54, s[64:65] offset:192
	s_waitcnt vmcnt(34)
	v_mfma_f32_16x16x32_bf16 v[16:19], v[170:173], v[194:197], v[16:19]
	global_load_dwordx4 v[166:169], v54, s[66:67] offset:128
	global_load_dwordx4 v[170:173], v54, s[66:67] offset:192
	s_waitcnt vmcnt(34)
	v_mfma_f32_16x16x32_bf16 v[12:15], v[178:181], v[194:197], v[12:15]
	global_load_dwordx4 v[174:177], v54, s[68:69] offset:128
	global_load_dwordx4 v[178:181], v54, s[68:69] offset:192
	s_waitcnt vmcnt(34)
	v_mfma_f32_16x16x32_bf16 v[8:11], v[186:189], v[194:197], v[8:11]
	global_load_dwordx4 v[182:185], v54, s[70:71] offset:128
	global_load_dwordx4 v[186:189], v54, s[70:71] offset:192
	v_add_u32_e32 v55, 0x1c30, v55
	s_waitcnt vmcnt(33)
	v_mfma_f32_16x16x32_bf16 v[36:39], v[62:65], v[198:201], v[36:39]
	s_waitcnt vmcnt(31)
	v_mfma_f32_16x16x32_bf16 v[32:35], v[70:73], v[198:201], v[32:35]
	s_waitcnt vmcnt(29)
	v_mfma_f32_16x16x32_bf16 v[28:31], v[78:81], v[198:201], v[28:31]
	s_waitcnt vmcnt(27)
	v_mfma_f32_16x16x32_bf16 v[24:27], v[86:89], v[198:201], v[24:27]
	s_waitcnt vmcnt(25)
	v_mfma_f32_16x16x32_bf16 v[20:23], v[94:97], v[198:201], v[20:23]
	s_waitcnt vmcnt(23)
	v_mfma_f32_16x16x32_bf16 v[16:19], v[102:105], v[198:201], v[16:19]
	s_waitcnt vmcnt(21)
	v_mfma_f32_16x16x32_bf16 v[12:15], v[110:113], v[198:201], v[12:15]
	s_waitcnt vmcnt(19)
	v_mfma_f32_16x16x32_bf16 v[8:11], v[118:121], v[198:201], v[8:11]
	s_waitcnt vmcnt(32)
	v_mfma_f32_16x16x32_bf16 v[36:39], v[66:69], v[202:205], v[36:39]
	s_waitcnt vmcnt(30)
	v_mfma_f32_16x16x32_bf16 v[32:35], v[74:77], v[202:205], v[32:35]
	s_waitcnt vmcnt(28)
	v_mfma_f32_16x16x32_bf16 v[28:31], v[82:85], v[202:205], v[28:31]
	s_waitcnt vmcnt(26)
	v_mfma_f32_16x16x32_bf16 v[24:27], v[90:93], v[202:205], v[24:27]
	s_waitcnt vmcnt(24)
	v_mfma_f32_16x16x32_bf16 v[20:23], v[98:101], v[202:205], v[20:23]
	s_waitcnt vmcnt(22)
	v_mfma_f32_16x16x32_bf16 v[16:19], v[106:109], v[202:205], v[16:19]
	s_waitcnt vmcnt(20)
	v_mfma_f32_16x16x32_bf16 v[12:15], v[114:117], v[202:205], v[12:15]
	s_waitcnt vmcnt(18)
	v_mfma_f32_16x16x32_bf16 v[8:11], v[122:125], v[202:205], v[8:11]
	s_waitcnt vmcnt(15)
	v_mfma_f32_16x16x32_bf16 v[36:39], v[126:129], v[206:209], v[36:39]
	s_waitcnt vmcnt(13)
	v_mfma_f32_16x16x32_bf16 v[32:35], v[134:137], v[206:209], v[32:35]
	s_waitcnt vmcnt(11)
	v_mfma_f32_16x16x32_bf16 v[28:31], v[142:145], v[206:209], v[28:31]
	s_waitcnt vmcnt(9)
	v_mfma_f32_16x16x32_bf16 v[24:27], v[150:153], v[206:209], v[24:27]
	s_waitcnt vmcnt(7)
	v_mfma_f32_16x16x32_bf16 v[20:23], v[158:161], v[206:209], v[20:23]
	s_waitcnt vmcnt(5)
	v_mfma_f32_16x16x32_bf16 v[16:19], v[166:169], v[206:209], v[16:19]
	s_waitcnt vmcnt(3)
	v_mfma_f32_16x16x32_bf16 v[12:15], v[174:177], v[206:209], v[12:15]
	s_waitcnt vmcnt(1)
	v_mfma_f32_16x16x32_bf16 v[8:11], v[182:185], v[206:209], v[8:11]
	s_waitcnt vmcnt(14)
; __device__ __forceinline__ float fast_rcp(float x) { return __builtin_amdgcn_rcpf(x); }
; #define MFMA16(a, b, c) __builtin_amdgcn_mfma_f32_16x16x32_bf16((a), (b), (c), 0, 0, 0)
; __device__ __forceinline__ void item_cmpk(const bf16_t* qkv, const bf16_t* Wb, const float* hb, bf16_t* KC, int it, int wsub) {
;     ...
;     for (int ks = 0; ks < 64; ++ks) {
;         const bf16x8 bfrag = *(const bf16x8*)(src + (size_t)(ks >> 1) * QP + (ks & 1) * 32);
; #pragma unroll
;         for (int ht = 0; ht < 8; ++ht) { const bf16x8 afrag = *(const bf16x8*)(w1t + (size_t)ht * 16 * 2048 + ks * 32); hT[ht] = MFMA16(afrag, bfrag, hT[ht]); }
;     }
; #pragma unroll
;     for (int ht = 0; ht < 8; ++ht)
; #pragma unroll
;         for (int j = 0; j < 4; ++j) { const float x = hT[ht][j] + hb[ty * 128 + 16 * ht + 4 * g + j]; const float u = 0.7978845608028654f * (x + 0.044715f * x * x * x);
;             const float th = 1.f - 2.f * fast_rcp(1.f + __expf(2.f * u)); hT[ht][j] = 0.5f * x * (1.f + th); }
	v_mfma_f32_16x16x32_bf16 v[36:39], v[130:133], v[210:213], v[36:39]
	s_waitcnt vmcnt(12)
	v_mfma_f32_16x16x32_bf16 v[32:35], v[138:141], v[210:213], v[32:35]
	s_waitcnt vmcnt(10)
	v_mfma_f32_16x16x32_bf16 v[28:31], v[146:149], v[210:213], v[28:31]
	s_waitcnt vmcnt(8)
	v_mfma_f32_16x16x32_bf16 v[24:27], v[154:157], v[210:213], v[24:27]
	s_waitcnt vmcnt(6)
	v_mfma_f32_16x16x32_bf16 v[20:23], v[162:165], v[210:213], v[20:23]
	s_waitcnt vmcnt(4)
	v_mfma_f32_16x16x32_bf16 v[16:19], v[170:173], v[210:213], v[16:19]
	s_waitcnt vmcnt(2)
	v_mfma_f32_16x16x32_bf16 v[12:15], v[178:181], v[210:213], v[12:15]
	s_waitcnt vmcnt(0)
	v_mfma_f32_16x16x32_bf16 v[8:11], v[186:189], v[210:213], v[8:11]
	v_and_b32_e32 v44, 3, v44
	v_lshlrev_b32_e32 v2, 4, v44
	v_readlane_b32 s0, v252, 16
	v_lshl_or_b32 v40, s6, 9, v2
	v_readlane_b32 s1, v252, 17
	v_lshlrev_b32_e32 v58, 8, v45
	v_mov_b32_e32 v59, v0
	s_nop 2
	global_load_dwordx4 v[46:49], v40, s[0:1]
	s_waitcnt vmcnt(0)
	v_pk_add_f32 v[2:3], v[36:37], v[46:47]
	s_nop 0
	v_mul_f32_e32 v36, 0x3d372713, v2
	v_mul_f32_e32 v37, 0x3d372713, v3
	v_mul_f32_e32 v36, v2, v36
	v_mul_f32_e32 v37, v3, v37
	v_fma_f32 v36, v2, v36, v2
	v_fma_f32 v37, v3, v37, v3
	v_mul_f32_e32 v36, 0x3f4c422a, v36
	v_mul_f32_e32 v37, 0x3f4c422a, v37
	v_add_f32_e32 v36, v36, v36
	v_add_f32_e32 v37, v37, v37
	v_mul_f32_e32 v36, 0x3fb8aa3b, v36
	v_mul_f32_e32 v37, 0x3fb8aa3b, v37
	v_exp_f32_e32 v36, v36
	v_exp_f32_e32 v37, v37
	v_pk_mul_f32 v[2:3], v[2:3], 0.5 op_sel_hi:[1,0]
	v_add_f32_e32 v36, 1.0, v36
	v_add_f32_e32 v37, 1.0, v37
	v_rcp_f32_e32 v36, v36
	v_rcp_f32_e32 v37, v37
	s_nop 0
	v_pk_fma_f32 v[36:37], v[36:37], 2.0, 1.0 op_sel_hi:[1,0,0] neg_lo:[1,0,0] neg_hi:[1,0,0]
	s_nop 0
	v_pk_add_f32 v[36:37], v[36:37], 1.0 op_sel_hi:[1,0]
	s_nop 0
	v_pk_mul_f32 v[2:3], v[2:3], v[36:37]
	v_pk_add_f32 v[36:37], v[38:39], v[48:49]
	global_load_dwordx4 v[46:49], v40, s[0:1] offset:64
	v_mul_f32_e32 v38, 0x3d372713, v36
	v_mul_f32_e32 v39, 0x3d372713, v37
	v_mul_f32_e32 v38, v36, v38
	v_mul_f32_e32 v39, v37, v39
	v_fma_f32 v38, v36, v38, v36
	v_fma_f32 v39, v37, v39, v37
	v_mul_f32_e32 v38, 0x3f4c422a, v38
	v_mul_f32_e32 v39, 0x3f4c422a, v39
	v_add_f32_e32 v38, v38, v38
	v_add_f32_e32 v39, v39, v39
	v_mul_f32_e32 v38, 0x3fb8aa3b, v38
	v_mul_f32_e32 v39, 0x3fb8aa3b, v39
	v_exp_f32_e32 v38, v38
	v_exp_f32_e32 v39, v39
	v_pk_mul_f32 v[36:37], v[36:37], 0.5 op_sel_hi:[1,0]
	v_add_f32_e32 v38, 1.0, v38
	v_add_f32_e32 v39, 1.0, v39
	v_rcp_f32_e32 v38, v38
	v_rcp_f32_e32 v39, v39
	s_waitcnt vmcnt(0)
	v_pk_add_f32 v[32:33], v[32:33], v[46:47]
	v_pk_add_f32 v[34:35], v[34:35], v[48:49]
	global_load_dwordx4 v[46:49], v40, s[0:1] offset:128
	v_pk_fma_f32 v[38:39], v[38:39], 2.0, 1.0 op_sel_hi:[1,0,0] neg_lo:[1,0,0] neg_hi:[1,0,0]
	s_waitcnt vmcnt(0)
	v_pk_add_f32 v[28:29], v[28:29], v[46:47]
	v_pk_add_f32 v[30:31], v[30:31], v[48:49]
	global_load_dwordx4 v[46:49], v40, s[0:1] offset:192
	v_pk_add_f32 v[38:39], v[38:39], 1.0 op_sel_hi:[1,0]
	s_waitcnt vmcnt(0)
	v_pk_add_f32 v[24:25], v[24:25], v[46:47]
	v_pk_add_f32 v[26:27], v[26:27], v[48:49]
	global_load_dwordx4 v[46:49], v40, s[0:1] offset:256
	v_pk_mul_f32 v[36:37], v[36:37], v[38:39]
	v_mul_f32_e32 v38, 0x3d372713, v32
	v_mul_f32_e32 v39, 0x3d372713, v33
	v_mul_f32_e32 v38, v32, v38
	v_mul_f32_e32 v39, v33, v39
	v_fma_f32 v38, v32, v38, v32
	v_fma_f32 v39, v33, v39, v33
	v_mul_f32_e32 v38, 0x3f4c422a, v38
	v_mul_f32_e32 v39, 0x3f4c422a, v39
	v_add_f32_e32 v38, v38, v38
	v_add_f32_e32 v39, v39, v39
	v_mul_f32_e32 v38, 0x3fb8aa3b, v38
	v_mul_f32_e32 v39, 0x3fb8aa3b, v39
	v_exp_f32_e32 v38, v38
	v_exp_f32_e32 v39, v39
	v_pk_mul_f32 v[32:33], v[32:33], 0.5 op_sel_hi:[1,0]
	v_add_f32_e32 v38, 1.0, v38
	v_add_f32_e32 v39, 1.0, v39
	v_rcp_f32_e32 v38, v38
	v_rcp_f32_e32 v39, v39
	s_waitcnt vmcnt(0)
	v_pk_add_f32 v[20:21], v[20:21], v[46:47]
	v_pk_add_f32 v[22:23], v[22:23], v[48:49]
	global_load_dwordx4 v[46:49], v40, s[0:1] offset:320
	v_pk_fma_f32 v[38:39], v[38:39], 2.0, 1.0 op_sel_hi:[1,0,0] neg_lo:[1,0,0] neg_hi:[1,0,0]
	s_waitcnt vmcnt(0)
	v_pk_add_f32 v[16:17], v[16:17], v[46:47]
	v_pk_add_f32 v[38:39], v[38:39], 1.0 op_sel_hi:[1,0]
	v_pk_add_f32 v[18:19], v[18:19], v[48:49]
	v_pk_mul_f32 v[32:33], v[32:33], v[38:39]
	v_mul_f32_e32 v38, 0x3d372713, v34
	v_mul_f32_e32 v39, 0x3d372713, v35
	v_mul_f32_e32 v38, v34, v38
	v_mul_f32_e32 v39, v35, v39
	v_fma_f32 v38, v34, v38, v34
	v_fma_f32 v39, v35, v39, v35
	v_mul_f32_e32 v38, 0x3f4c422a, v38
	v_mul_f32_e32 v39, 0x3f4c422a, v39
	v_add_f32_e32 v38, v38, v38
	v_add_f32_e32 v39, v39, v39
	v_mul_f32_e32 v38, 0x3fb8aa3b, v38
	v_mul_f32_e32 v39, 0x3fb8aa3b, v39
	v_exp_f32_e32 v38, v38
	v_exp_f32_e32 v39, v39
	v_pk_mul_f32 v[34:35], v[34:35], 0.5 op_sel_hi:[1,0]
	global_load_dwordx4 v[46:49], v40, s[0:1] offset:384
	v_add_f32_e32 v38, 1.0, v38
	v_add_f32_e32 v39, 1.0, v39
	v_rcp_f32_e32 v38, v38
	v_rcp_f32_e32 v39, v39
	s_waitcnt vmcnt(0)
; __device__ __forceinline__ unsigned cvtpk(float lo, float hi) { f32x2 v = {lo, hi}; bf16x2_t b = __builtin_convertvector(v, bf16x2_t); return __builtin_bit_cast(unsigned, b); }
; __device__ __forceinline__ float fast_rcp(float x) { return __builtin_amdgcn_rcpf(x); }
; __device__ __forceinline__ void item_cmpk(const bf16_t* qkv, const bf16_t* Wb, const float* hb, bf16_t* KC, int it, int wsub) {
;     ...
;     for (int ht = 0; ht < 8; ++ht)
; #pragma unroll
;         for (int j = 0; j < 4; ++j) { const float x = hT[ht][j] + hb[ty * 128 + 16 * ht + 4 * g + j]; const float u = 0.7978845608028654f * (x + 0.044715f * x * x * x);
;             const float th = 1.f - 2.f * fast_rcp(1.f + __expf(2.f * u)); hT[ht][j] = 0.5f * x * (1.f + th); }
;     f32x4 oT[4];
; #pragma unroll
;     for (int dt = 0; dt < 4; ++dt) oT[dt] = (f32x4){0.f, 0.f, 0.f, 0.f};
;     const bf16_t* w2t = Wb + W_2 + (size_t)ty * 64 * 128;
; #pragma unroll
;     for (int p = 0; p < 4; ++p) { u32x4 w; w.x = cvtpk(hT[2 * p][0], hT[2 * p][1]); w.y = cvtpk(hT[2 * p][2], hT[2 * p][3]); w.z = cvtpk(hT[2 * p + 1][0], hT[2 * p + 1][1]); w.w = cvtpk(hT[2 * p + 1][2], hT[2 * p + 1][3]);
	v_pk_add_f32 v[12:13], v[12:13], v[46:47]
	v_pk_fma_f32 v[38:39], v[38:39], 2.0, 1.0 op_sel_hi:[1,0,0] neg_lo:[1,0,0] neg_hi:[1,0,0]
	v_pk_add_f32 v[14:15], v[14:15], v[48:49]
	v_pk_add_f32 v[38:39], v[38:39], 1.0 op_sel_hi:[1,0]
	s_nop 0
	v_pk_mul_f32 v[34:35], v[34:35], v[38:39]
	v_mul_f32_e32 v38, 0x3d372713, v28
	v_mul_f32_e32 v39, 0x3d372713, v29
	v_mul_f32_e32 v38, v28, v38
	v_mul_f32_e32 v39, v29, v39
	v_fma_f32 v38, v28, v38, v28
	v_fma_f32 v39, v29, v39, v29
	v_mul_f32_e32 v38, 0x3f4c422a, v38
	v_mul_f32_e32 v39, 0x3f4c422a, v39
	v_add_f32_e32 v38, v38, v38
	v_add_f32_e32 v39, v39, v39
	v_mul_f32_e32 v38, 0x3fb8aa3b, v38
	v_mul_f32_e32 v39, 0x3fb8aa3b, v39
	v_exp_f32_e32 v38, v38
	v_exp_f32_e32 v39, v39
	v_pk_mul_f32 v[28:29], v[28:29], 0.5 op_sel_hi:[1,0]
	v_add_f32_e32 v38, 1.0, v38
	v_add_f32_e32 v39, 1.0, v39
	v_rcp_f32_e32 v38, v38
	v_rcp_f32_e32 v39, v39
	s_nop 0
	v_pk_fma_f32 v[38:39], v[38:39], 2.0, 1.0 op_sel_hi:[1,0,0] neg_lo:[1,0,0] neg_hi:[1,0,0]
	s_nop 0
	v_pk_add_f32 v[38:39], v[38:39], 1.0 op_sel_hi:[1,0]
	s_nop 0
	v_pk_mul_f32 v[28:29], v[28:29], v[38:39]
	v_mul_f32_e32 v38, 0x3d372713, v30
	v_mul_f32_e32 v39, 0x3d372713, v31
	v_mul_f32_e32 v38, v30, v38
	v_mul_f32_e32 v39, v31, v39
	v_fma_f32 v38, v30, v38, v30
	v_fma_f32 v39, v31, v39, v31
	v_mul_f32_e32 v38, 0x3f4c422a, v38
	v_mul_f32_e32 v39, 0x3f4c422a, v39
	v_add_f32_e32 v38, v38, v38
	v_add_f32_e32 v39, v39, v39
	v_mul_f32_e32 v38, 0x3fb8aa3b, v38
	v_mul_f32_e32 v39, 0x3fb8aa3b, v39
	v_exp_f32_e32 v38, v38
	v_exp_f32_e32 v39, v39
	v_pk_mul_f32 v[30:31], v[30:31], 0.5 op_sel_hi:[1,0]
	v_cvt_pk_bf16_f32 v28, v28, v29
	v_add_f32_e32 v38, 1.0, v38
	v_add_f32_e32 v39, 1.0, v39
	v_rcp_f32_e32 v38, v38
	v_rcp_f32_e32 v39, v39
	s_nop 0
	v_pk_fma_f32 v[38:39], v[38:39], 2.0, 1.0 op_sel_hi:[1,0,0] neg_lo:[1,0,0] neg_hi:[1,0,0]
	s_nop 0
	v_pk_add_f32 v[38:39], v[38:39], 1.0 op_sel_hi:[1,0]
	s_nop 0
	v_pk_mul_f32 v[30:31], v[30:31], v[38:39]
	v_mul_f32_e32 v38, 0x3d372713, v24
	v_mul_f32_e32 v39, 0x3d372713, v25
	v_mul_f32_e32 v38, v24, v38
	v_mul_f32_e32 v39, v25, v39
	v_fma_f32 v38, v24, v38, v24
	v_fma_f32 v39, v25, v39, v25
	v_mul_f32_e32 v38, 0x3f4c422a, v38
	v_mul_f32_e32 v39, 0x3f4c422a, v39
	v_add_f32_e32 v38, v38, v38
	v_add_f32_e32 v39, v39, v39
	v_mul_f32_e32 v38, 0x3fb8aa3b, v38
	v_mul_f32_e32 v39, 0x3fb8aa3b, v39
	v_exp_f32_e32 v38, v38
	v_exp_f32_e32 v39, v39
	v_pk_mul_f32 v[24:25], v[24:25], 0.5 op_sel_hi:[1,0]
	v_cvt_pk_bf16_f32 v29, v30, v31
	v_add_f32_e32 v38, 1.0, v38
	v_add_f32_e32 v39, 1.0, v39
	v_rcp_f32_e32 v38, v38
	v_rcp_f32_e32 v39, v39
	s_nop 0
	v_pk_fma_f32 v[38:39], v[38:39], 2.0, 1.0 op_sel_hi:[1,0,0] neg_lo:[1,0,0] neg_hi:[1,0,0]
	s_nop 0
	v_pk_add_f32 v[38:39], v[38:39], 1.0 op_sel_hi:[1,0]
	s_nop 0
	v_pk_mul_f32 v[24:25], v[24:25], v[38:39]
	v_mul_f32_e32 v38, 0x3d372713, v26
	v_mul_f32_e32 v39, 0x3d372713, v27
	v_mul_f32_e32 v38, v26, v38
	v_mul_f32_e32 v39, v27, v39
	v_fma_f32 v38, v26, v38, v26
	v_fma_f32 v39, v27, v39, v27
	v_mul_f32_e32 v38, 0x3f4c422a, v38
	v_mul_f32_e32 v39, 0x3f4c422a, v39
	v_add_f32_e32 v38, v38, v38
	v_add_f32_e32 v39, v39, v39
	v_mul_f32_e32 v38, 0x3fb8aa3b, v38
	v_mul_f32_e32 v39, 0x3fb8aa3b, v39
	v_exp_f32_e32 v38, v38
	v_exp_f32_e32 v39, v39
	v_pk_mul_f32 v[26:27], v[26:27], 0.5 op_sel_hi:[1,0]
	v_cvt_pk_bf16_f32 v30, v24, v25
	v_add_f32_e32 v38, 1.0, v38
	v_add_f32_e32 v39, 1.0, v39
	v_rcp_f32_e32 v38, v38
	v_rcp_f32_e32 v39, v39
	s_nop 0
	v_pk_fma_f32 v[38:39], v[38:39], 2.0, 1.0 op_sel_hi:[1,0,0] neg_lo:[1,0,0] neg_hi:[1,0,0]
	s_nop 0
	v_pk_add_f32 v[38:39], v[38:39], 1.0 op_sel_hi:[1,0]
	s_nop 0
	v_pk_mul_f32 v[26:27], v[26:27], v[38:39]
	v_mul_f32_e32 v38, 0x3d372713, v20
	v_mul_f32_e32 v39, 0x3d372713, v21
	v_mul_f32_e32 v38, v20, v38
	v_mul_f32_e32 v39, v21, v39
	v_fma_f32 v38, v20, v38, v20
	v_fma_f32 v39, v21, v39, v21
	v_mul_f32_e32 v38, 0x3f4c422a, v38
	v_mul_f32_e32 v39, 0x3f4c422a, v39
	v_add_f32_e32 v38, v38, v38
	v_add_f32_e32 v39, v39, v39
	v_mul_f32_e32 v38, 0x3fb8aa3b, v38
	v_mul_f32_e32 v39, 0x3fb8aa3b, v39
	v_exp_f32_e32 v38, v38
	v_exp_f32_e32 v39, v39
	v_pk_mul_f32 v[20:21], v[20:21], 0.5 op_sel_hi:[1,0]
	v_cvt_pk_bf16_f32 v31, v26, v27
	v_add_f32_e32 v38, 1.0, v38
	v_add_f32_e32 v39, 1.0, v39
	v_rcp_f32_e32 v38, v38
	v_rcp_f32_e32 v39, v39
	s_nop 0
	v_pk_fma_f32 v[38:39], v[38:39], 2.0, 1.0 op_sel_hi:[1,0,0] neg_lo:[1,0,0] neg_hi:[1,0,0]
	s_nop 0
	v_pk_add_f32 v[38:39], v[38:39], 1.0 op_sel_hi:[1,0]
	s_nop 0
	v_pk_mul_f32 v[20:21], v[20:21], v[38:39]
	v_mul_f32_e32 v38, 0x3d372713, v22
	v_mul_f32_e32 v39, 0x3d372713, v23
	v_mul_f32_e32 v38, v22, v38
	v_mul_f32_e32 v39, v23, v39
	v_fma_f32 v38, v22, v38, v22
	v_fma_f32 v39, v23, v39, v23
	v_mul_f32_e32 v38, 0x3f4c422a, v38
	v_mul_f32_e32 v39, 0x3f4c422a, v39
	v_add_f32_e32 v38, v38, v38
	v_add_f32_e32 v39, v39, v39
	v_mul_f32_e32 v38, 0x3fb8aa3b, v38
	v_mul_f32_e32 v39, 0x3fb8aa3b, v39
	v_exp_f32_e32 v38, v38
	v_exp_f32_e32 v39, v39
	v_pk_mul_f32 v[22:23], v[22:23], 0.5 op_sel_hi:[1,0]
	v_cvt_pk_bf16_f32 v20, v20, v21
	v_add_f32_e32 v38, 1.0, v38
	v_add_f32_e32 v39, 1.0, v39
	v_rcp_f32_e32 v38, v38
	v_rcp_f32_e32 v39, v39
	s_nop 0
	v_pk_fma_f32 v[38:39], v[38:39], 2.0, 1.0 op_sel_hi:[1,0,0] neg_lo:[1,0,0] neg_hi:[1,0,0]
	s_nop 0
	v_pk_add_f32 v[38:39], v[38:39], 1.0 op_sel_hi:[1,0]
	s_nop 0
	v_pk_mul_f32 v[22:23], v[22:23], v[38:39]
	v_mul_f32_e32 v38, 0x3d372713, v16
	v_mul_f32_e32 v39, 0x3d372713, v17
	v_mul_f32_e32 v38, v16, v38
	v_mul_f32_e32 v39, v17, v39
	v_fma_f32 v38, v16, v38, v16
	v_fma_f32 v39, v17, v39, v17
	v_mul_f32_e32 v38, 0x3f4c422a, v38
	v_mul_f32_e32 v39, 0x3f4c422a, v39
	v_add_f32_e32 v38, v38, v38
; __device__ __forceinline__ unsigned cvtpk(float lo, float hi) { f32x2 v = {lo, hi}; bf16x2_t b = __builtin_convertvector(v, bf16x2_t); return __builtin_bit_cast(unsigned, b); }
; __device__ __forceinline__ float fast_rcp(float x) { return __builtin_amdgcn_rcpf(x); }
; __device__ __forceinline__ void item_cmpk(const bf16_t* qkv, const bf16_t* Wb, const float* hb, bf16_t* KC, int it, int wsub) {
;     ...
;         for (int j = 0; j < 4; ++j) { const float x = hT[ht][j] + hb[ty * 128 + 16 * ht + 4 * g + j]; const float u = 0.7978845608028654f * (x + 0.044715f * x * x * x);
;             const float th = 1.f - 2.f * fast_rcp(1.f + __expf(2.f * u)); hT[ht][j] = 0.5f * x * (1.f + th); }
;     f32x4 oT[4];
; #pragma unroll
;     for (int dt = 0; dt < 4; ++dt) oT[dt] = (f32x4){0.f, 0.f, 0.f, 0.f};
;     const bf16_t* w2t = Wb + W_2 + (size_t)ty * 64 * 128;
; #pragma unroll
;     for (int p = 0; p < 4; ++p) { u32x4 w; w.x = cvtpk(hT[2 * p][0], hT[2 * p][1]); w.y = cvtpk(hT[2 * p][2], hT[2 * p][3]); w.z = cvtpk(hT[2 * p + 1][0], hT[2 * p + 1][1]); w.w = cvtpk(hT[2 * p + 1][2], hT[2 * p + 1][3]);
;         const bf16x8 bfrag = __builtin_bit_cast(bf16x8, w);
; #pragma unroll
;         for (int dt = 0; dt < 4; ++dt) { const bf16_t* ap = w2t + (size_t)(16 * dt + c) * 128 + 32 * p + 4 * g; const u32x2 a0 = *(const u32x2*)ap, a1 = *(const u32x2*)(ap + 16);
	v_add_f32_e32 v39, v39, v39
	v_mul_f32_e32 v38, 0x3fb8aa3b, v38
	v_mul_f32_e32 v39, 0x3fb8aa3b, v39
	v_exp_f32_e32 v38, v38
	v_exp_f32_e32 v39, v39
	v_pk_mul_f32 v[16:17], v[16:17], 0.5 op_sel_hi:[1,0]
	v_cvt_pk_bf16_f32 v21, v22, v23
	v_add_f32_e32 v38, 1.0, v38
	v_add_f32_e32 v39, 1.0, v39
	v_rcp_f32_e32 v38, v38
	v_rcp_f32_e32 v39, v39
	s_nop 0
	v_pk_fma_f32 v[38:39], v[38:39], 2.0, 1.0 op_sel_hi:[1,0,0] neg_lo:[1,0,0] neg_hi:[1,0,0]
	s_nop 0
	v_pk_add_f32 v[38:39], v[38:39], 1.0 op_sel_hi:[1,0]
	s_nop 0
	v_pk_mul_f32 v[16:17], v[16:17], v[38:39]
	v_mul_f32_e32 v38, 0x3d372713, v18
	v_mul_f32_e32 v39, 0x3d372713, v19
	v_mul_f32_e32 v38, v18, v38
	v_mul_f32_e32 v39, v19, v39
	v_fma_f32 v38, v18, v38, v18
	v_fma_f32 v39, v19, v39, v19
	v_mul_f32_e32 v38, 0x3f4c422a, v38
	v_mul_f32_e32 v39, 0x3f4c422a, v39
	v_add_f32_e32 v38, v38, v38
	v_add_f32_e32 v39, v39, v39
	v_mul_f32_e32 v38, 0x3fb8aa3b, v38
	v_mul_f32_e32 v39, 0x3fb8aa3b, v39
	v_exp_f32_e32 v38, v38
	v_exp_f32_e32 v39, v39
	v_pk_mul_f32 v[18:19], v[18:19], 0.5 op_sel_hi:[1,0]
	v_cvt_pk_bf16_f32 v22, v16, v17
	v_add_f32_e32 v38, 1.0, v38
	v_add_f32_e32 v39, 1.0, v39
	v_rcp_f32_e32 v38, v38
	v_rcp_f32_e32 v39, v39
	s_nop 0
	v_pk_fma_f32 v[38:39], v[38:39], 2.0, 1.0 op_sel_hi:[1,0,0] neg_lo:[1,0,0] neg_hi:[1,0,0]
	s_nop 0
	v_pk_add_f32 v[38:39], v[38:39], 1.0 op_sel_hi:[1,0]
	s_nop 0
	v_pk_mul_f32 v[18:19], v[18:19], v[38:39]
	v_mul_f32_e32 v38, 0x3d372713, v12
	v_mul_f32_e32 v39, 0x3d372713, v13
	v_mul_f32_e32 v38, v12, v38
	v_mul_f32_e32 v39, v13, v39
	v_fma_f32 v38, v12, v38, v12
	v_fma_f32 v39, v13, v39, v13
	v_mul_f32_e32 v38, 0x3f4c422a, v38
	v_mul_f32_e32 v39, 0x3f4c422a, v39
	v_add_f32_e32 v38, v38, v38
	v_add_f32_e32 v39, v39, v39
	v_mul_f32_e32 v38, 0x3fb8aa3b, v38
	v_mul_f32_e32 v39, 0x3fb8aa3b, v39
	v_exp_f32_e32 v38, v38
	v_exp_f32_e32 v39, v39
	v_pk_mul_f32 v[12:13], v[12:13], 0.5 op_sel_hi:[1,0]
	v_cvt_pk_bf16_f32 v23, v18, v19
	v_add_f32_e32 v38, 1.0, v38
	v_add_f32_e32 v39, 1.0, v39
	v_rcp_f32_e32 v38, v38
	v_rcp_f32_e32 v39, v39
	s_nop 0
	v_pk_fma_f32 v[38:39], v[38:39], 2.0, 1.0 op_sel_hi:[1,0,0] neg_lo:[1,0,0] neg_hi:[1,0,0]
	s_nop 0
	v_pk_add_f32 v[38:39], v[38:39], 1.0 op_sel_hi:[1,0]
	s_nop 0
	v_pk_mul_f32 v[12:13], v[12:13], v[38:39]
	v_mul_f32_e32 v38, 0x3d372713, v14
	v_mul_f32_e32 v39, 0x3d372713, v15
	v_mul_f32_e32 v38, v14, v38
	v_mul_f32_e32 v39, v15, v39
	v_fma_f32 v38, v14, v38, v14
	v_fma_f32 v39, v15, v39, v15
	v_mul_f32_e32 v38, 0x3f4c422a, v38
	v_mul_f32_e32 v39, 0x3f4c422a, v39
	v_add_f32_e32 v38, v38, v38
	v_add_f32_e32 v39, v39, v39
	v_mul_f32_e32 v38, 0x3fb8aa3b, v38
	v_mul_f32_e32 v39, 0x3fb8aa3b, v39
	v_exp_f32_e32 v38, v38
	v_exp_f32_e32 v39, v39
	v_pk_mul_f32 v[14:15], v[14:15], 0.5 op_sel_hi:[1,0]
	v_cvt_pk_bf16_f32 v12, v12, v13
	v_add_f32_e32 v38, 1.0, v38
	v_add_f32_e32 v39, 1.0, v39
	v_rcp_f32_e32 v38, v38
	v_rcp_f32_e32 v39, v39
	s_nop 0
	v_pk_fma_f32 v[38:39], v[38:39], 2.0, 1.0 op_sel_hi:[1,0,0] neg_lo:[1,0,0] neg_hi:[1,0,0]
	s_nop 0
	v_pk_add_f32 v[38:39], v[38:39], 1.0 op_sel_hi:[1,0]
	s_nop 0
	v_pk_mul_f32 v[14:15], v[14:15], v[38:39]
	global_load_dwordx4 v[38:41], v40, s[0:1] offset:448
	s_lshl_b32 s0, s6, 14
	v_readlane_b32 s1, v252, 40
	s_add_u32 s0, s1, s0
	v_readlane_b32 s1, v252, 41
	s_addc_u32 s1, s1, 0
	v_cvt_pk_bf16_f32 v13, v14, v15
	s_waitcnt vmcnt(0)
	v_pk_add_f32 v[8:9], v[8:9], v[38:39]
	s_nop 0
	v_mul_f32_e32 v38, 0x3d372713, v8
	v_mul_f32_e32 v39, 0x3d372713, v9
	v_mul_f32_e32 v38, v8, v38
	v_mul_f32_e32 v39, v9, v39
	v_fma_f32 v38, v8, v38, v8
	v_fma_f32 v39, v9, v39, v9
	v_mul_f32_e32 v38, 0x3f4c422a, v38
	v_mul_f32_e32 v39, 0x3f4c422a, v39
	v_add_f32_e32 v38, v38, v38
	v_add_f32_e32 v39, v39, v39
	v_mul_f32_e32 v38, 0x3fb8aa3b, v38
	v_mul_f32_e32 v39, 0x3fb8aa3b, v39
	v_exp_f32_e32 v38, v38
	v_exp_f32_e32 v39, v39
	v_pk_mul_f32 v[8:9], v[8:9], 0.5 op_sel_hi:[1,0]
	v_add_f32_e32 v38, 1.0, v38
	v_add_f32_e32 v39, 1.0, v39
	v_rcp_f32_e32 v38, v38
	v_rcp_f32_e32 v39, v39
	s_nop 0
	v_pk_fma_f32 v[38:39], v[38:39], 2.0, 1.0 op_sel_hi:[1,0,0] neg_lo:[1,0,0] neg_hi:[1,0,0]
	s_nop 0
	v_pk_add_f32 v[38:39], v[38:39], 1.0 op_sel_hi:[1,0]
	s_nop 0
	v_pk_mul_f32 v[38:39], v[8:9], v[38:39]
	v_pk_add_f32 v[8:9], v[10:11], v[40:41]
	v_cvt_pk_bf16_f32 v14, v38, v39
	v_mul_f32_e32 v10, 0x3d372713, v8
	v_mul_f32_e32 v11, 0x3d372713, v9
	v_mul_f32_e32 v10, v8, v10
	v_mul_f32_e32 v11, v9, v11
	v_fma_f32 v10, v8, v10, v8
	v_fma_f32 v11, v9, v11, v9
	v_mul_f32_e32 v10, 0x3f4c422a, v10
	v_mul_f32_e32 v11, 0x3f4c422a, v11
	v_add_f32_e32 v10, v10, v10
	v_add_f32_e32 v11, v11, v11
	v_mul_f32_e32 v10, 0x3fb8aa3b, v10
	v_mul_f32_e32 v11, 0x3fb8aa3b, v11
	v_exp_f32_e32 v10, v10
	v_exp_f32_e32 v11, v11
	v_pk_mul_f32 v[8:9], v[8:9], 0.5 op_sel_hi:[1,0]
	v_add_f32_e32 v10, 1.0, v10
	v_add_f32_e32 v11, 1.0, v11
	v_rcp_f32_e32 v10, v10
	v_rcp_f32_e32 v11, v11
	s_nop 0
	v_pk_fma_f32 v[10:11], v[10:11], 2.0, 1.0 op_sel_hi:[1,0,0] neg_lo:[1,0,0] neg_hi:[1,0,0]
	s_nop 0
	v_pk_add_f32 v[10:11], v[10:11], 1.0 op_sel_hi:[1,0]
	s_nop 0
	v_pk_mul_f32 v[40:41], v[8:9], v[10:11]
	v_lshlrev_b32_e32 v8, 3, v44
	v_mov_b32_e32 v9, v0
	v_lshl_add_u64 v[42:43], s[0:1], 0, v[8:9]
	v_cvt_pk_bf16_f32 v9, v36, v37
	v_lshl_add_u64 v[36:37], v[42:43], 0, v[58:59]
	v_cvt_pk_bf16_f32 v10, v32, v33
	v_cvt_pk_bf16_f32 v11, v34, v35
	global_load_dwordx2 v[32:33], v[36:37], off
	global_load_dwordx2 v[34:35], v[36:37], off offset:32
	v_cvt_pk_bf16_f32 v8, v2, v3
	s_mov_b64 s[0:1], 0xc0
	v_cvt_pk_bf16_f32 v15, v40, v41
	s_waitcnt vmcnt(0)
; __device__ __forceinline__ unsigned cvtpk(float lo, float hi) { f32x2 v = {lo, hi}; bf16x2_t b = __builtin_convertvector(v, bf16x2_t); return __builtin_bit_cast(unsigned, b); }
; #define MFMA16(a, b, c) __builtin_amdgcn_mfma_f32_16x16x32_bf16((a), (b), (c), 0, 0, 0)
; __device__ __forceinline__ void item_cmpk(const bf16_t* qkv, const bf16_t* Wb, const float* hb, bf16_t* KC, int it, int wsub) {
;     ...
; #pragma unroll
;     for (int p = 0; p < 4; ++p) { u32x4 w; w.x = cvtpk(hT[2 * p][0], hT[2 * p][1]); w.y = cvtpk(hT[2 * p][2], hT[2 * p][3]); w.z = cvtpk(hT[2 * p + 1][0], hT[2 * p + 1][1]); w.w = cvtpk(hT[2 * p + 1][2], hT[2 * p + 1][3]);
;         const bf16x8 bfrag = __builtin_bit_cast(bf16x8, w);
; #pragma unroll
;         for (int dt = 0; dt < 4; ++dt) { const bf16_t* ap = w2t + (size_t)(16 * dt + c) * 128 + 32 * p + 4 * g; const u32x2 a0 = *(const u32x2*)ap, a1 = *(const u32x2*)(ap + 16);
;             u32x4 aw; aw.x = a0.x; aw.y = a0.y; aw.z = a1.x; aw.w = a1.y; oT[dt] = MFMA16(__builtin_bit_cast(bf16x8, aw), bfrag, oT[dt]); } }
;     if (n < 127) { bf16_t* dst = KC + ((((size_t)ty * 32 + b) * 2 + gk) * 128 + n) * 64;
; #pragma unroll
;         for (int dt = 0; dt < 4; ++dt) { u32x2 w; w.x = cvtpk(oT[dt][0], oT[dt][1]); w.y = cvtpk(oT[dt][2], oT[dt][3]); *(u32x2*)(dst + 16 * dt + 4 * g) = w; } }
	v_mfma_f32_16x16x32_bf16 v[46:49], v[32:35], v[8:11], 0
	v_or_b32_e32 v34, 0x1000, v58
	v_mov_b32_e32 v35, v0
	v_lshl_add_u64 v[2:3], v[42:43], 0, v[34:35]
	global_load_dwordx2 v[50:51], v[2:3], off
	global_load_dwordx2 v[52:53], v[2:3], off offset:32
	v_or_b32_e32 v2, 0x2000, v58
	v_mov_b32_e32 v3, v0
	v_lshl_add_u64 v[32:33], v[42:43], 0, v[2:3]
	global_load_dwordx2 v[54:55], v[32:33], off
	global_load_dwordx2 v[56:57], v[32:33], off offset:32
	v_or_b32_e32 v32, 0x3000, v58
	v_mov_b32_e32 v33, v0
	v_lshl_add_u64 v[60:61], v[42:43], 0, v[32:33]
	global_load_dwordx2 v[58:59], v[60:61], off
	s_nop 0
	global_load_dwordx2 v[60:61], v[60:61], off offset:32
	s_nop 0
	global_load_dwordx2 v[24:25], v[36:37], off offset:64
	global_load_dwordx2 v[26:27], v[36:37], off offset:96
	s_waitcnt vmcnt(6)
	v_mfma_f32_16x16x32_bf16 v[50:53], v[50:53], v[8:11], 0
	s_waitcnt vmcnt(4)
	v_mfma_f32_16x16x32_bf16 v[54:57], v[54:57], v[8:11], 0
	s_waitcnt vmcnt(2)
	v_mfma_f32_16x16x32_bf16 v[8:11], v[58:61], v[8:11], 0
	v_lshl_add_u64 v[58:59], v[42:43], 0, 64
	s_waitcnt vmcnt(0)
	v_mfma_f32_16x16x32_bf16 v[24:27], v[24:27], v[28:31], v[46:49]
	s_nop 2
	v_lshl_add_u64 v[48:49], v[58:59], 0, v[34:35]
	global_load_dwordx2 v[46:47], v[48:49], off
	s_nop 0
	global_load_dwordx2 v[48:49], v[48:49], off offset:32
	s_waitcnt vmcnt(0)
	v_mfma_f32_16x16x32_bf16 v[46:49], v[46:49], v[28:31], v[50:53]
	s_nop 2
	v_lshl_add_u64 v[52:53], v[58:59], 0, v[2:3]
	global_load_dwordx2 v[50:51], v[52:53], off
	s_nop 0
	global_load_dwordx2 v[52:53], v[52:53], off offset:32
	s_waitcnt vmcnt(0)
	v_mfma_f32_16x16x32_bf16 v[50:53], v[50:53], v[28:31], v[54:57]
	s_nop 2
	v_lshl_add_u64 v[56:57], v[58:59], 0, v[32:33]
	global_load_dwordx2 v[54:55], v[56:57], off
	s_nop 0
	global_load_dwordx2 v[56:57], v[56:57], off offset:32
	s_nop 0
	global_load_dwordx2 v[16:17], v[36:37], off offset:128
	global_load_dwordx2 v[18:19], v[36:37], off offset:160
	s_waitcnt vmcnt(2)
	v_mfma_f32_16x16x32_bf16 v[8:11], v[54:57], v[28:31], v[8:11]
	v_lshl_add_u64 v[28:29], v[42:43], 0, s[30:31]
	v_lshl_add_u64 v[30:31], v[28:29], 0, v[32:33]
	s_waitcnt vmcnt(0)
	v_mfma_f32_16x16x32_bf16 v[24:27], v[16:19], v[20:23], v[24:27]
	v_lshl_add_u64 v[18:19], v[28:29], 0, v[34:35]
	global_load_dwordx2 v[16:17], v[18:19], off
	s_nop 0
	global_load_dwordx2 v[18:19], v[18:19], off offset:32
	s_waitcnt vmcnt(0)
	v_mfma_f32_16x16x32_bf16 v[46:49], v[16:19], v[20:23], v[46:49]
	v_lshl_add_u64 v[18:19], v[28:29], 0, v[2:3]
	global_load_dwordx2 v[16:17], v[18:19], off
	s_nop 0
	global_load_dwordx2 v[18:19], v[18:19], off offset:32
	s_nop 0
	global_load_dwordx2 v[28:29], v[30:31], off
	s_nop 0
	global_load_dwordx2 v[30:31], v[30:31], off offset:32
	s_waitcnt vmcnt(2)
	v_mfma_f32_16x16x32_bf16 v[16:19], v[16:19], v[20:23], v[50:53]
	s_waitcnt vmcnt(0)
	v_mfma_f32_16x16x32_bf16 v[8:11], v[28:31], v[20:23], v[8:11]
	global_load_dwordx2 v[20:21], v[36:37], off offset:192
	global_load_dwordx2 v[22:23], v[36:37], off offset:224
	v_lshl_add_u64 v[28:29], v[42:43], 0, s[0:1]
	v_lshl_add_u64 v[2:3], v[28:29], 0, v[2:3]
	s_waitcnt vmcnt(0)
	v_mfma_f32_16x16x32_bf16 v[20:23], v[20:23], v[12:15], v[24:27]
	s_nop 2
	v_lshl_add_u64 v[26:27], v[28:29], 0, v[34:35]
	global_load_dwordx2 v[24:25], v[26:27], off
	s_nop 0
	global_load_dwordx2 v[26:27], v[26:27], off offset:32
	s_nop 0
	global_load_dwordx2 v[34:35], v[2:3], off
	global_load_dwordx2 v[36:37], v[2:3], off offset:32
	v_lshl_add_u64 v[2:3], v[28:29], 0, v[32:33]
	global_load_dwordx2 v[28:29], v[2:3], off
	global_load_dwordx2 v[30:31], v[2:3], off offset:32
	s_waitcnt vmcnt(4)
	v_mfma_f32_16x16x32_bf16 v[24:27], v[24:27], v[12:15], v[46:49]
	s_waitcnt vmcnt(2)
	v_mfma_f32_16x16x32_bf16 v[16:19], v[34:37], v[12:15], v[16:19]
	s_waitcnt vmcnt(0)
	v_mfma_f32_16x16x32_bf16 v[8:11], v[28:31], v[12:15], v[8:11]
	s_and_saveexec_b64 s[0:1], vcc
	s_xor_b64 s[0:1], exec, s[0:1]
	s_cbranch_execz .LBB0_246
	s_and_b32 s7, s7, 1
	s_lshl_b32 s6, s6, 6
	s_lshl_b64 s[4:5], s[4:5], 1
	s_add_u32 s4, s6, s4
	s_addc_u32 s5, 0, s5
	s_or_b32 s4, s4, s7
	s_lshl_b64 s[4:5], s[4:5], 14
	v_readlane_b32 s6, v252, 12
	s_add_u32 s4, s6, s4
	v_readlane_b32 s6, v252, 13
	v_lshlrev_b32_e32 v12, 2, v44
	s_addc_u32 s5, s6, s5
	v_lshlrev_b32_e32 v2, 7, v1
	v_mov_b32_e32 v3, v0
	v_lshl_add_u64 v[2:3], s[4:5], 0, v[2:3]
	v_lshlrev_b32_e32 v12, 1, v12
	v_mov_b32_e32 v13, v0
	v_lshl_add_u64 v[2:3], v[2:3], 0, v[12:13]
	v_cvt_pk_bf16_f32 v12, v20, v21
	v_cvt_pk_bf16_f32 v13, v22, v23
	global_store_dwordx2 v[2:3], v[12:13], off
	v_cvt_pk_bf16_f32 v12, v24, v25
	v_cvt_pk_bf16_f32 v13, v26, v27
	global_store_dwordx2 v[2:3], v[12:13], off offset:32
	v_cvt_pk_bf16_f32 v12, v16, v17
	v_cvt_pk_bf16_f32 v13, v18, v19
	v_cvt_pk_bf16_f32 v8, v8, v9
	v_cvt_pk_bf16_f32 v9, v10, v11
	global_store_dwordx2 v[2:3], v[12:13], off offset:64
	global_store_dwordx2 v[2:3], v[8:9], off offset:96
	s_branch .LBB0_246
